# P6 split-K (extra row panel) epilogue: next row scale load issued before the four slab stores of the round, wait vmcnt(4) instead of vmcnt(0)
# baseline (speedup 1.0000x reference)
.LBB0_1241:
	s_bfe_u32 s38, s66, 0x80008
	s_lshl_b32 s8, s38, 8
	v_mov_b32_e32 v16, v176
	v_mov_b32_e32 v42, v175
	s_or_b32 s8, s8, s50
	s_and_b32 s37, s66, 0xf0000
	v_lshl_add_u32 v156, v16, 3, s8
	v_ashrrev_i32_e32 v157, 31, v156
	v_lshl_add_u64 v[40:41], v[156:157], 2, s[16:17]
	global_load_dwordx4 v[16:19], v[40:41], off
	global_load_dwordx4 v[24:27], v[40:41], off offset:16
	global_load_dwordx4 v[162:165], v[40:41], off offset:512
	global_load_dwordx4 v[166:169], v[40:41], off offset:528
	s_lshl_b32 s8, s66, 8
	s_and_b32 s36, s8, 0xff00
	v_add_u32_e32 v172, s49, v42
	v_add_u32_e32 v160, s36, v172
	s_cmp_eq_u32 s37, 0
	v_ashrrev_i32_e32 v161, 31, v160
	s_waitcnt vmcnt(0)
	v_pk_mul_f32 v[88:89], v[16:17], s[26:27] op_sel_hi:[1,0]
	v_pk_mul_f32 v[40:41], v[24:25], s[26:27] op_sel_hi:[1,0]
	v_pk_mul_f32 v[24:25], v[162:163], s[26:27] op_sel_hi:[1,0]
	v_pk_mul_f32 v[16:17], v[166:167], s[26:27] op_sel_hi:[1,0]
	v_pk_mul_f32 v[90:91], v[18:19], s[26:27] op_sel_hi:[1,0]
	v_pk_mul_f32 v[42:43], v[26:27], s[26:27] op_sel_hi:[1,0]
	v_pk_mul_f32 v[26:27], v[164:165], s[26:27] op_sel_hi:[1,0]
	v_pk_mul_f32 v[18:19], v[168:169], s[26:27] op_sel_hi:[1,0]
	v_pk_mul_f32 v[170:171], v[88:89], v[140:141]
	v_pk_mul_f32 v[168:169], v[40:41], v[142:143]
	v_pk_mul_f32 v[166:167], v[24:25], v[144:145]
	v_pk_mul_f32 v[164:165], v[16:17], v[146:147]
	v_pk_mul_f32 v[162:163], v[88:89], v[116:117]
	v_pk_mul_f32 v[150:151], v[40:41], v[112:113]
	v_pk_mul_f32 v[146:147], v[24:25], v[114:115]
	v_pk_mul_f32 v[144:145], v[16:17], v[118:119]
	v_pk_mul_f32 v[142:143], v[88:89], v[104:105]
	v_pk_mul_f32 v[140:141], v[40:41], v[96:97]
	v_pk_mul_f32 v[118:119], v[24:25], v[148:149]
	v_pk_mul_f32 v[116:117], v[16:17], v[152:153]
	v_pk_mul_f32 v[114:115], v[88:89], v[98:99]
	v_pk_mul_f32 v[112:113], v[40:41], v[106:107]
	v_pk_mul_f32 v[106:107], v[24:25], v[154:155]
	v_pk_mul_f32 v[98:99], v[16:17], v[158:159]
	s_cbranch_scc1 .LBB0_1248
	v_lshl_add_u64 v[96:97], v[160:161], 2, s[14:15]
	global_load_dword v148, v[96:97], off
	s_lshr_b32 s8, s66, 13
	v_ashrrev_i32_e32 v173, 31, v172
	s_and_b32 s8, s8, 0x7f80
	v_mov_b64_e32 v[96:97], s[82:83]
	v_add_u32_e32 v192, 16, v172
	v_lshl_add_u64 v[180:181], v[172:173], 0, s[8:9]
	v_add_u32_e32 v154, s36, v192
	v_mad_u64_u32 v[182:183], s[40:41], v180, s61, v[96:97]
	v_lshlrev_b64 v[104:105], 2, v[156:157]
	v_pk_mul_f32 v[152:153], v[90:91], v[124:125]
	v_ashrrev_i32_e32 v155, 31, v154
	v_mad_i32_i24 v183, v181, s61, v183
	v_pk_mul_f32 v[158:159], v[42:43], v[120:121]
	v_pk_mul_f32 v[184:185], v[26:27], v[122:123]
	v_pk_mul_f32 v[188:189], v[18:19], v[126:127]
	v_lshl_add_u64 v[194:195], v[154:155], 2, s[14:15]
	v_lshl_add_u64 v[196:197], v[182:183], 0, v[104:105]
	v_ashrrev_i32_e32 v193, 31, v192
	s_waitcnt vmcnt(0)
	v_pk_mul_f32 v[154:155], v[152:153], v[148:149] op_sel_hi:[1,0]
	v_pk_mul_f32 v[152:153], v[170:171], v[148:149] op_sel_hi:[1,0]
	v_pk_mul_f32 v[182:183], v[158:159], v[148:149] op_sel_hi:[1,0]
	v_pk_mul_f32 v[180:181], v[168:169], v[148:149] op_sel_hi:[1,0]
	v_pk_mul_f32 v[186:187], v[184:185], v[148:149] op_sel_hi:[1,0]
	v_pk_mul_f32 v[184:185], v[166:167], v[148:149] op_sel_hi:[1,0]
	v_pk_mul_f32 v[190:191], v[188:189], v[148:149] op_sel_hi:[1,0]
	v_pk_mul_f32 v[188:189], v[164:165], v[148:149] op_sel_hi:[1,0]
	global_load_dword v148, v[194:195], off
	global_store_dwordx4 v[196:197], v[152:155], off
	global_store_dwordx4 v[196:197], v[180:183], off offset:16
	global_store_dwordx4 v[196:197], v[184:187], off offset:512
	global_store_dwordx4 v[196:197], v[188:191], off offset:528
	v_add_u32_e32 v194, 32, v172
	v_lshl_add_u64 v[180:181], v[192:193], 0, s[8:9]
	v_add_u32_e32 v154, s36, v194
	v_mad_u64_u32 v[182:183], s[40:41], v180, s61, v[96:97]
	v_pk_mul_f32 v[152:153], v[90:91], v[108:109]
	v_ashrrev_i32_e32 v155, 31, v154
	v_mad_i32_i24 v183, v181, s61, v183
	v_pk_mul_f32 v[158:159], v[42:43], v[110:111]
	v_pk_mul_f32 v[184:185], v[26:27], v[100:101]
	v_pk_mul_f32 v[188:189], v[18:19], v[102:103]
	v_lshl_add_u64 v[192:193], v[154:155], 2, s[14:15]
	v_lshl_add_u64 v[196:197], v[182:183], 0, v[104:105]
	v_ashrrev_i32_e32 v195, 31, v194
	v_add_u32_e32 v172, 48, v172
	v_ashrrev_i32_e32 v173, 31, v172
	s_waitcnt vmcnt(4)
	v_pk_mul_f32 v[154:155], v[152:153], v[148:149] op_sel_hi:[1,0]
	v_pk_mul_f32 v[152:153], v[162:163], v[148:149] op_sel_hi:[1,0]
	v_pk_mul_f32 v[182:183], v[158:159], v[148:149] op_sel_hi:[1,0]
	v_pk_mul_f32 v[180:181], v[150:151], v[148:149] op_sel_hi:[1,0]
	v_pk_mul_f32 v[186:187], v[184:185], v[148:149] op_sel_hi:[1,0]
	v_pk_mul_f32 v[184:185], v[146:147], v[148:149] op_sel_hi:[1,0]
	v_pk_mul_f32 v[190:191], v[188:189], v[148:149] op_sel_hi:[1,0]
	v_pk_mul_f32 v[188:189], v[144:145], v[148:149] op_sel_hi:[1,0]
	global_load_dword v148, v[192:193], off
	global_store_dwordx4 v[196:197], v[152:155], off
	global_store_dwordx4 v[196:197], v[180:183], off offset:16
	global_store_dwordx4 v[196:197], v[184:187], off offset:512
	global_store_dwordx4 v[196:197], v[188:191], off offset:528
	v_lshl_add_u64 v[180:181], v[194:195], 0, s[8:9]
	v_add_u32_e32 v154, s36, v172
	v_mad_u64_u32 v[182:183], s[36:37], v180, s61, v[96:97]
	v_pk_mul_f32 v[152:153], v[90:91], v[84:85]
	v_ashrrev_i32_e32 v155, 31, v154
	v_mad_i32_i24 v183, v181, s61, v183
	v_pk_mul_f32 v[158:159], v[42:43], v[86:87]
	v_pk_mul_f32 v[184:185], v[26:27], v[92:93]
	v_pk_mul_f32 v[188:189], v[18:19], v[94:95]
	v_lshl_add_u64 v[192:193], v[154:155], 2, s[14:15]
	v_lshl_add_u64 v[194:195], v[182:183], 0, v[104:105]
	s_waitcnt vmcnt(4)
	v_pk_mul_f32 v[154:155], v[152:153], v[148:149] op_sel_hi:[1,0]
	v_pk_mul_f32 v[152:153], v[142:143], v[148:149] op_sel_hi:[1,0]
	v_pk_mul_f32 v[182:183], v[158:159], v[148:149] op_sel_hi:[1,0]
	v_pk_mul_f32 v[180:181], v[140:141], v[148:149] op_sel_hi:[1,0]
	v_pk_mul_f32 v[186:187], v[184:185], v[148:149] op_sel_hi:[1,0]
	v_pk_mul_f32 v[184:185], v[118:119], v[148:149] op_sel_hi:[1,0]
	v_pk_mul_f32 v[190:191], v[188:189], v[148:149] op_sel_hi:[1,0]
	v_pk_mul_f32 v[188:189], v[116:117], v[148:149] op_sel_hi:[1,0]
	global_load_dword v148, v[192:193], off
	global_store_dwordx4 v[194:195], v[152:155], off
	global_store_dwordx4 v[194:195], v[180:183], off offset:16
	global_store_dwordx4 v[194:195], v[184:187], off offset:512
	global_store_dwordx4 v[194:195], v[188:191], off offset:528
	v_lshl_add_u64 v[154:155], v[172:173], 0, s[8:9]
	v_mad_u64_u32 v[96:97], s[36:37], v154, s61, v[96:97]
	v_pk_mul_f32 v[152:153], v[90:91], v[76:77]
	v_mad_i32_i24 v97, v155, s61, v97
	v_pk_mul_f32 v[158:159], v[42:43], v[78:79]
	v_pk_mul_f32 v[184:185], v[26:27], v[80:81]
	v_pk_mul_f32 v[188:189], v[18:19], v[82:83]
	v_lshl_add_u64 v[96:97], v[96:97], 0, v[104:105]
	s_waitcnt vmcnt(4)
	v_pk_mul_f32 v[154:155], v[152:153], v[148:149] op_sel_hi:[1,0]
	v_pk_mul_f32 v[152:153], v[114:115], v[148:149] op_sel_hi:[1,0]
	v_pk_mul_f32 v[182:183], v[158:159], v[148:149] op_sel_hi:[1,0]
	v_pk_mul_f32 v[180:181], v[112:113], v[148:149] op_sel_hi:[1,0]
	v_pk_mul_f32 v[186:187], v[184:185], v[148:149] op_sel_hi:[1,0]
	v_pk_mul_f32 v[184:185], v[106:107], v[148:149] op_sel_hi:[1,0]
	v_pk_mul_f32 v[190:191], v[188:189], v[148:149] op_sel_hi:[1,0]
	v_pk_mul_f32 v[188:189], v[98:99], v[148:149] op_sel_hi:[1,0]
	global_store_dwordx4 v[96:97], v[152:155], off
	global_store_dwordx4 v[96:97], v[180:183], off offset:16
	global_store_dwordx4 v[96:97], v[184:187], off offset:512
	global_store_dwordx4 v[96:97], v[188:191], off offset:528
	s_cbranch_execnz .LBB0_1244
